# attention tile loop: one schedule for all waves (stagger variant removed) with the static priority raise for waves 4-7
# speedup vs baseline: 1.0013x; 1.0013x over previous
; #define LAS __attribute__((address_space(3)))
; __device__ __forceinline__ unsigned pk2(float lo, float hi) { f32x2_t v = {lo, hi}; bf16x2_t b = __builtin_convertvector(v, bf16x2_t); return __builtin_bit_cast(unsigned, b); }
; __device__ __forceinline__ void dsa_unit32(const Args& a, LAS unsigned char* lds, const LAS unsigned long long* maskl, int b, int qb, int tid, int wave, int lane) {
;     ...
;     auto compute = [&](int buf, int kt) {
;         const unsigned long long mw = maskl[l31 * 32 + kt];
;         const LAS bf16* Ks = (const LAS bf16*)(lds + buf * STG); const LAS bf16* Vs = (const LAS bf16*)(lds + buf * STG + KBYTES);
;         f32x16 S2[2];
; #pragma unroll
;         for (int kh = 0; kh < 2; ++kh) {
; #pragma unroll
;             for (int i = 0; i < 16; ++i) S2[kh][i] = negB;
;             __builtin_amdgcn_s_setprio(1);
; #pragma unroll
;             for (int ks = 0; ks < 8; ++ks) S2[kh] = mfma32(*(const LAS bf16x8*)(Ks + (32 * kh + l31) * KS + 16 * ks + 8 * hi), qf[ks], S2[kh]);
;             __builtin_amdgcn_s_setprio(0);
;         }
; #pragma unroll
;         for (int kh = 0; kh < 2; ++kh) {
;             const unsigned mh = (unsigned)(mw >> (32 * kh + 4 * hi));
;             float p[16];
; #pragma unroll
;             for (int i = 0; i < 16; ++i) { const float e = __builtin_amdgcn_exp2f(S2[kh][i]);
;                 const int keep = __builtin_amdgcn_sbfe((int)mh, 8 * (i >> 2) + (i & 3), 1);
;                 p[i] = __builtin_bit_cast(float, __builtin_bit_cast(int, e) & keep); l += p[i]; }
;             u32x4 w0, w1;
;             w0.x = pk2(p[0], p[1]); w0.y = pk2(p[2], p[3]); w0.z = pk2(p[4], p[5]); w0.w = pk2(p[6], p[7]);
;             w1.x = pk2(p[8], p[9]); w1.y = pk2(p[10], p[11]); w1.z = pk2(p[12], p[13]); w1.w = pk2(p[14], p[15]);
;             const bf16x8 pa = __builtin_bit_cast(bf16x8, w0), pb = __builtin_bit_cast(bf16x8, w1);
;             __builtin_amdgcn_s_setprio(1);
; #pragma unroll
;             for (int ct = 0; ct < 4; ++ct) {
;                 const LAS bf16* vr = Vs + (32 * ct + l31) * VS + 4 * hi + 32 * kh;
;                 O[ct] = mfma32(cat8(*(const LAS u32x2*)(vr), *(const LAS u32x2*)(vr + 8)), pa, O[ct]);
;                 O[ct] = mfma32(cat8(*(const LAS u32x2*)(vr + 16), *(const LAS u32x2*)(vr + 24)), pb, O[ct]);
;             }
;             __builtin_amdgcn_s_setprio(0);
;         }
;     ...
;         compute(0, kt);
.LBB0_1304:
	v_add_u32_e32 v207, -8, v206
	ds_read_b64 v[220:221], v207
	v_add_u32_e32 v207, v202, v180
	ds_read_b128 v[216:219], v207 offset:0
	ds_read_b128 v[228:231], v207 offset:32
	ds_read_b128 v[232:235], v207 offset:64
	ds_read_b128 v[236:239], v207 offset:96
	ds_read_b128 v[240:243], v207 offset:128
	ds_read_b128 v[244:247], v207 offset:160
	ds_read_b128 v[248:251], v207 offset:192
	ds_read_b128 v[222:225], v207 offset:224
	ds_read_b128 v[208:211], v207 offset:8704
	ds_read_b128 v[212:215], v207 offset:8736
	s_waitcnt lgkmcnt(9)
	v_mfma_f32_32x32x16_bf16 v[102:117], v[216:219], v[126:129], v[70:85]
	ds_read_b128 v[216:219], v207 offset:8768
	s_waitcnt lgkmcnt(9)
	v_mfma_f32_32x32x16_bf16 v[102:117], v[228:231], v[0:3], v[102:117]
	ds_read_b128 v[228:231], v207 offset:8800
	s_waitcnt lgkmcnt(9)
	v_mfma_f32_32x32x16_bf16 v[102:117], v[232:235], v[118:121], v[102:117]
	ds_read_b128 v[232:235], v207 offset:8832
	s_waitcnt lgkmcnt(9)
	v_mfma_f32_32x32x16_bf16 v[102:117], v[236:239], v[122:125], v[102:117]
	ds_read_b128 v[236:239], v207 offset:8864
	s_waitcnt lgkmcnt(9)
	v_mfma_f32_32x32x16_bf16 v[102:117], v[240:243], v[130:133], v[102:117]
	ds_read_b128 v[240:243], v207 offset:8896
	s_waitcnt lgkmcnt(9)
	v_mfma_f32_32x32x16_bf16 v[102:117], v[244:247], v[134:137], v[102:117]
	ds_read_b128 v[244:247], v207 offset:8928
	s_waitcnt lgkmcnt(9)
	v_mfma_f32_32x32x16_bf16 v[102:117], v[248:251], v[138:141], v[102:117]
	s_waitcnt lgkmcnt(8)
	v_mfma_f32_32x32x16_bf16 v[102:117], v[222:225], v[142:145], v[102:117]
	s_waitcnt lgkmcnt(7)
	v_mfma_f32_32x32x16_bf16 v[86:101], v[208:211], v[126:129], v[70:85]
	s_waitcnt lgkmcnt(6)
	v_mfma_f32_32x32x16_bf16 v[86:101], v[212:215], v[0:3], v[86:101]
	s_waitcnt lgkmcnt(5)
	v_mfma_f32_32x32x16_bf16 v[86:101], v[216:219], v[118:121], v[86:101]
	ds_read_b128 v[248:251], v203 offset:17408
	ds_read_b128 v[222:225], v203 offset:17440
	ds_read_b128 v[216:219], v203 offset:22016
	s_waitcnt lgkmcnt(7)
	v_mfma_f32_32x32x16_bf16 v[86:101], v[228:231], v[122:125], v[86:101]
	ds_read_b128 v[228:231], v203 offset:22048
	s_waitcnt lgkmcnt(7)
	v_mfma_f32_32x32x16_bf16 v[86:101], v[232:235], v[130:133], v[86:101]
	ds_read_b128 v[232:235], v203 offset:26624
	s_waitcnt lgkmcnt(7)
	v_mfma_f32_32x32x16_bf16 v[86:101], v[236:239], v[134:137], v[86:101]
	ds_read_b128 v[236:239], v203 offset:26656
	s_waitcnt lgkmcnt(7)
	v_mfma_f32_32x32x16_bf16 v[86:101], v[240:243], v[138:141], v[86:101]
	ds_read_b128 v[240:243], v203 offset:31232
	s_waitcnt lgkmcnt(7)
	v_mfma_f32_32x32x16_bf16 v[86:101], v[244:247], v[142:145], v[86:101]
	ds_read_b128 v[244:247], v203 offset:31264
	v_lshrrev_b64 v[208:209], v182, v[220:221]
	v_exp_f32_e32 v102, v102
	v_bfe_i32 v209, v208, 0, 1
	v_exp_f32_e32 v103, v103
	v_bfe_i32 v210, v208, 1, 1
	v_and_b32_e32 v102, v102, v209
	v_exp_f32_e32 v104, v104
	v_bfe_i32 v211, v208, 2, 1
	v_and_b32_e32 v103, v103, v210
	v_exp_f32_e32 v105, v105
	v_bfe_i32 v209, v208, 3, 1
	v_and_b32_e32 v104, v104, v211
	v_exp_f32_e32 v106, v106
	v_bfe_i32 v210, v208, 8, 1
	v_and_b32_e32 v105, v105, v209
	v_exp_f32_e32 v107, v107
	v_bfe_i32 v211, v208, 9, 1
	v_and_b32_e32 v106, v106, v210
	v_exp_f32_e32 v108, v108
	v_bfe_i32 v209, v208, 10, 1
	v_and_b32_e32 v107, v107, v211
	v_exp_f32_e32 v109, v109
	v_bfe_i32 v210, v208, 11, 1
	v_and_b32_e32 v108, v108, v209
	v_exp_f32_e32 v110, v110
	v_bfe_i32 v211, v208, 16, 1
	v_and_b32_e32 v109, v109, v210
	v_exp_f32_e32 v111, v111
	v_bfe_i32 v209, v208, 17, 1
	v_and_b32_e32 v110, v110, v211
	v_exp_f32_e32 v112, v112
	v_bfe_i32 v210, v208, 18, 1
	v_and_b32_e32 v111, v111, v209
	v_exp_f32_e32 v113, v113
	v_bfe_i32 v211, v208, 19, 1
	v_and_b32_e32 v112, v112, v210
	v_exp_f32_e32 v114, v114
	v_bfe_i32 v209, v208, 24, 1
	v_and_b32_e32 v113, v113, v211
	v_exp_f32_e32 v115, v115
	v_bfe_i32 v210, v208, 25, 1
	v_and_b32_e32 v114, v114, v209
	v_exp_f32_e32 v116, v116
	v_bfe_i32 v211, v208, 26, 1
	v_and_b32_e32 v115, v115, v210
	v_exp_f32_e32 v117, v117
	v_bfe_i32 v209, v208, 27, 1
	v_and_b32_e32 v116, v116, v211
	s_nop 0
	v_and_b32_e32 v117, v117, v209
	v_cvt_pk_bf16_f32 v208, v102, v103
	v_cvt_pk_bf16_f32 v209, v104, v105
	v_cvt_pk_bf16_f32 v210, v106, v107
	v_cvt_pk_bf16_f32 v211, v108, v109
	v_cvt_pk_bf16_f32 v212, v110, v111
	v_cvt_pk_bf16_f32 v213, v112, v113
	v_cvt_pk_bf16_f32 v214, v114, v115
	v_cvt_pk_bf16_f32 v215, v116, v117
	s_nop 1
	s_waitcnt lgkmcnt(7)
	v_mfma_f32_32x32x16_bf16 v[54:69], v[248:251], v[208:211], v[54:69]
	ds_read_b128 v[248:251], v203 offset:17472
	v_add_f32_e32 v194, v194, v102
	v_add_f32_e32 v194, v103, v194
	s_waitcnt lgkmcnt(7)
; #define LAS __attribute__((address_space(3)))
; __device__ __forceinline__ unsigned pk2(float lo, float hi) { f32x2_t v = {lo, hi}; bf16x2_t b = __builtin_convertvector(v, bf16x2_t); return __builtin_bit_cast(unsigned, b); }
; __device__ __forceinline__ f32x16 mfma32(bf16x8 a, bf16x8 b, f32x16 c) { return __builtin_amdgcn_mfma_f32_32x32x16_bf16(a, b, c, 0, 0, 0); }
; __device__ __forceinline__ void dsa_unit32(const Args& a, LAS unsigned char* lds, const LAS unsigned long long* maskl, int b, int qb, int tid, int wave, int lane) {
;     ...
;         for (int kh = 0; kh < 2; ++kh) {
;             const unsigned mh = (unsigned)(mw >> (32 * kh + 4 * hi));
;             float p[16];
; #pragma unroll
;             for (int i = 0; i < 16; ++i) { const float e = __builtin_amdgcn_exp2f(S2[kh][i]);
;                 const int keep = __builtin_amdgcn_sbfe((int)mh, 8 * (i >> 2) + (i & 3), 1);
;                 p[i] = __builtin_bit_cast(float, __builtin_bit_cast(int, e) & keep); l += p[i]; }
;             u32x4 w0, w1;
;             w0.x = pk2(p[0], p[1]); w0.y = pk2(p[2], p[3]); w0.z = pk2(p[4], p[5]); w0.w = pk2(p[6], p[7]);
;             w1.x = pk2(p[8], p[9]); w1.y = pk2(p[10], p[11]); w1.z = pk2(p[12], p[13]); w1.w = pk2(p[14], p[15]);
;             const bf16x8 pa = __builtin_bit_cast(bf16x8, w0), pb = __builtin_bit_cast(bf16x8, w1);
;             __builtin_amdgcn_s_setprio(1);
; #pragma unroll
;             for (int ct = 0; ct < 4; ++ct) {
;                 const LAS bf16* vr = Vs + (32 * ct + l31) * VS + 4 * hi + 32 * kh;
;                 O[ct] = mfma32(cat8(*(const LAS u32x2*)(vr), *(const LAS u32x2*)(vr + 8)), pa, O[ct]);
;                 O[ct] = mfma32(cat8(*(const LAS u32x2*)(vr + 16), *(const LAS u32x2*)(vr + 24)), pb, O[ct]);
;             }
;             __builtin_amdgcn_s_setprio(0);
;         }
;     };
;     DSA_GLOAD(0, rk0, rv0); if (nkt > 1) DSA_GLOAD(1, rk1, rv1);
;     DSA_LSTORE(0, rk0, rv0);
;     __syncthreads();
; #pragma unroll 1
;     for (int kt = 0; kt < nkt; kt += 2) {
;         if (kt + 2 < nkt) DSA_GLOAD(kt + 2, rk0, rv0);
;         compute(0, kt);
;         if (kt + 1 < nkt) DSA_LSTORE(1, rk1, rv1);
	v_mfma_f32_32x32x16_bf16 v[54:69], v[222:225], v[212:215], v[54:69]
	ds_read_b128 v[222:225], v203 offset:17504
	v_add_f32_e32 v194, v104, v194
	v_add_f32_e32 v194, v105, v194
	s_waitcnt lgkmcnt(7)
	v_mfma_f32_32x32x16_bf16 v[38:53], v[216:219], v[208:211], v[38:53]
	ds_read_b128 v[216:219], v203 offset:22080
	v_add_f32_e32 v194, v106, v194
	v_add_f32_e32 v194, v107, v194
	s_waitcnt lgkmcnt(7)
	v_mfma_f32_32x32x16_bf16 v[38:53], v[228:231], v[212:215], v[38:53]
	ds_read_b128 v[228:231], v203 offset:22112
	v_add_f32_e32 v194, v108, v194
	v_add_f32_e32 v194, v109, v194
	s_waitcnt lgkmcnt(7)
	v_mfma_f32_32x32x16_bf16 v[22:37], v[232:235], v[208:211], v[22:37]
	ds_read_b128 v[232:235], v203 offset:26688
	v_add_f32_e32 v194, v110, v194
	v_add_f32_e32 v194, v111, v194
	s_waitcnt lgkmcnt(7)
	v_mfma_f32_32x32x16_bf16 v[22:37], v[236:239], v[212:215], v[22:37]
	ds_read_b128 v[236:239], v203 offset:26720
	v_add_f32_e32 v194, v112, v194
	v_add_f32_e32 v194, v113, v194
	s_waitcnt lgkmcnt(7)
	v_mfma_f32_32x32x16_bf16 v[6:21], v[240:243], v[208:211], v[6:21]
	ds_read_b128 v[240:243], v203 offset:31296
	v_add_f32_e32 v194, v114, v194
	v_add_f32_e32 v194, v115, v194
	s_waitcnt lgkmcnt(7)
	v_mfma_f32_32x32x16_bf16 v[6:21], v[244:247], v[212:215], v[6:21]
	ds_read_b128 v[244:247], v203 offset:31328
	v_add_f32_e32 v194, v116, v194
	v_add_f32_e32 v194, v117, v194
	v_lshrrev_b64 v[208:209], v184, v[220:221]
	v_exp_f32_e32 v86, v86
	v_bfe_i32 v209, v208, 0, 1
	v_exp_f32_e32 v87, v87
	v_bfe_i32 v210, v208, 1, 1
	v_and_b32_e32 v86, v86, v209
	v_exp_f32_e32 v88, v88
	v_bfe_i32 v211, v208, 2, 1
	v_and_b32_e32 v87, v87, v210
	v_exp_f32_e32 v89, v89
	v_bfe_i32 v209, v208, 3, 1
	v_and_b32_e32 v88, v88, v211
	v_exp_f32_e32 v90, v90
	v_bfe_i32 v210, v208, 8, 1
	v_and_b32_e32 v89, v89, v209
	v_exp_f32_e32 v91, v91
	v_bfe_i32 v211, v208, 9, 1
	v_and_b32_e32 v90, v90, v210
	v_exp_f32_e32 v92, v92
	v_bfe_i32 v209, v208, 10, 1
	v_and_b32_e32 v91, v91, v211
	v_exp_f32_e32 v93, v93
	v_bfe_i32 v210, v208, 11, 1
	v_and_b32_e32 v92, v92, v209
	v_exp_f32_e32 v94, v94
	v_bfe_i32 v211, v208, 16, 1
	v_and_b32_e32 v93, v93, v210
	v_exp_f32_e32 v95, v95
	v_bfe_i32 v209, v208, 17, 1
	v_and_b32_e32 v94, v94, v211
	v_exp_f32_e32 v96, v96
	v_bfe_i32 v210, v208, 18, 1
	v_and_b32_e32 v95, v95, v209
	v_exp_f32_e32 v97, v97
	v_bfe_i32 v211, v208, 19, 1
	v_and_b32_e32 v96, v96, v210
	v_exp_f32_e32 v98, v98
	v_bfe_i32 v209, v208, 24, 1
	v_and_b32_e32 v97, v97, v211
	v_exp_f32_e32 v99, v99
	v_bfe_i32 v210, v208, 25, 1
	v_and_b32_e32 v98, v98, v209
	v_exp_f32_e32 v100, v100
	v_bfe_i32 v211, v208, 26, 1
	v_and_b32_e32 v99, v99, v210
	v_exp_f32_e32 v101, v101
	v_bfe_i32 v209, v208, 27, 1
	v_and_b32_e32 v100, v100, v211
	s_nop 0
	v_and_b32_e32 v101, v101, v209
	v_cvt_pk_bf16_f32 v208, v86, v87
	v_cvt_pk_bf16_f32 v209, v88, v89
	v_cvt_pk_bf16_f32 v210, v90, v91
	v_cvt_pk_bf16_f32 v211, v92, v93
	v_cvt_pk_bf16_f32 v212, v94, v95
	v_cvt_pk_bf16_f32 v213, v96, v97
	v_cvt_pk_bf16_f32 v214, v98, v99
	v_cvt_pk_bf16_f32 v215, v100, v101
	s_nop 1
	s_waitcnt lgkmcnt(7)
	v_mfma_f32_32x32x16_bf16 v[54:69], v[248:251], v[208:211], v[54:69]
	v_add_f32_e32 v194, v194, v86
	v_add_f32_e32 v194, v87, v194
	s_waitcnt lgkmcnt(6)
	v_mfma_f32_32x32x16_bf16 v[54:69], v[222:225], v[212:215], v[54:69]
	v_add_f32_e32 v194, v88, v194
	v_add_f32_e32 v194, v89, v194
	s_waitcnt lgkmcnt(5)
	v_mfma_f32_32x32x16_bf16 v[38:53], v[216:219], v[208:211], v[38:53]
	v_add_f32_e32 v194, v90, v194
	v_add_f32_e32 v194, v91, v194
	s_waitcnt lgkmcnt(4)
	v_mfma_f32_32x32x16_bf16 v[38:53], v[228:231], v[212:215], v[38:53]
	v_add_f32_e32 v194, v92, v194
	v_add_f32_e32 v194, v93, v194
	s_waitcnt lgkmcnt(3)
	v_mfma_f32_32x32x16_bf16 v[22:37], v[232:235], v[208:211], v[22:37]
	v_add_f32_e32 v194, v94, v194
	v_add_f32_e32 v194, v95, v194
	s_waitcnt lgkmcnt(2)
	v_mfma_f32_32x32x16_bf16 v[22:37], v[236:239], v[212:215], v[22:37]
	v_add_f32_e32 v194, v96, v194
	v_add_f32_e32 v194, v97, v194
	s_waitcnt lgkmcnt(1)
	v_mfma_f32_32x32x16_bf16 v[6:21], v[240:243], v[208:211], v[6:21]
	v_add_f32_e32 v194, v98, v194
	v_add_f32_e32 v194, v99, v194
	s_waitcnt lgkmcnt(0)
	v_mfma_f32_32x32x16_bf16 v[6:21], v[244:247], v[212:215], v[6:21]
	v_add_f32_e32 v194, v100, v194
	v_add_f32_e32 v194, v101, v194
	s_add_i32 s7, s5, -2
	s_cmp_lt_u32 s7, s4
	s_cselect_b64 s[2:3], -1, 0
	s_cmp_ge_u32 s7, s4
	s_cbranch_scc1 .LBB0_1306
	s_mov_b32 s7, 0xd400
	v_add3_u32 v208, v195, v197, s7
	s_waitcnt vmcnt(3)
	ds_write_b128 v196, v[162:165] offset:36864
	s_waitcnt vmcnt(1)
	ds_write2_b64 v208, v[170:171], v[172:173] offset1:2
	ds_write_b128 v199, v[166:169] offset:36864
	v_add3_u32 v208, v195, v200, s7
	s_waitcnt vmcnt(0)
	ds_write2_b64 v208, v[174:175], v[176:177] offset1:2

; #define LAS __attribute__((address_space(3)))
; __device__ __forceinline__ unsigned pk2(float lo, float hi) { f32x2_t v = {lo, hi}; bf16x2_t b = __builtin_convertvector(v, bf16x2_t); return __builtin_bit_cast(unsigned, b); }
; __device__ __forceinline__ void dsa_unit32(const Args& a, LAS unsigned char* lds, const LAS unsigned long long* maskl, int b, int qb, int tid, int wave, int lane) {
;     ...
;     auto compute = [&](int buf, int kt) {
;         const unsigned long long mw = maskl[l31 * 32 + kt];
;         const LAS bf16* Ks = (const LAS bf16*)(lds + buf * STG); const LAS bf16* Vs = (const LAS bf16*)(lds + buf * STG + KBYTES);
;         f32x16 S2[2];
; #pragma unroll
;         for (int kh = 0; kh < 2; ++kh) {
; #pragma unroll
;             for (int i = 0; i < 16; ++i) S2[kh][i] = negB;
;             __builtin_amdgcn_s_setprio(1);
; #pragma unroll
;             for (int ks = 0; ks < 8; ++ks) S2[kh] = mfma32(*(const LAS bf16x8*)(Ks + (32 * kh + l31) * KS + 16 * ks + 8 * hi), qf[ks], S2[kh]);
;             __builtin_amdgcn_s_setprio(0);
;         }
; #pragma unroll
;         for (int kh = 0; kh < 2; ++kh) {
;             const unsigned mh = (unsigned)(mw >> (32 * kh + 4 * hi));
;             float p[16];
; #pragma unroll
;             for (int i = 0; i < 16; ++i) { const float e = __builtin_amdgcn_exp2f(S2[kh][i]);
;                 const int keep = __builtin_amdgcn_sbfe((int)mh, 8 * (i >> 2) + (i & 3), 1);
;                 p[i] = __builtin_bit_cast(float, __builtin_bit_cast(int, e) & keep); l += p[i]; }
;             u32x4 w0, w1;
;             w0.x = pk2(p[0], p[1]); w0.y = pk2(p[2], p[3]); w0.z = pk2(p[4], p[5]); w0.w = pk2(p[6], p[7]);
;             w1.x = pk2(p[8], p[9]); w1.y = pk2(p[10], p[11]); w1.z = pk2(p[12], p[13]); w1.w = pk2(p[14], p[15]);
;             const bf16x8 pa = __builtin_bit_cast(bf16x8, w0), pb = __builtin_bit_cast(bf16x8, w1);
;             __builtin_amdgcn_s_setprio(1);
; #pragma unroll
;             for (int ct = 0; ct < 4; ++ct) {
;                 const LAS bf16* vr = Vs + (32 * ct + l31) * VS + 4 * hi + 32 * kh;
;                 O[ct] = mfma32(cat8(*(const LAS u32x2*)(vr), *(const LAS u32x2*)(vr + 8)), pa, O[ct]);
;                 O[ct] = mfma32(cat8(*(const LAS u32x2*)(vr + 16), *(const LAS u32x2*)(vr + 24)), pb, O[ct]);
;             }
;             __builtin_amdgcn_s_setprio(0);
;         }
;     ...
;         compute(1, kt + 1);
.LBB0_1309:
	ds_read_b64 v[220:221], v206
	v_add_u32_e32 v207, v202, v180
	ds_read_b128 v[216:219], v207 offset:36864
	ds_read_b128 v[228:231], v207 offset:36896
	ds_read_b128 v[232:235], v207 offset:36928
	ds_read_b128 v[236:239], v207 offset:36960
	ds_read_b128 v[240:243], v207 offset:36992
	ds_read_b128 v[244:247], v207 offset:37024
	ds_read_b128 v[248:251], v207 offset:37056
	ds_read_b128 v[222:225], v207 offset:37088
	ds_read_b128 v[208:211], v207 offset:45568
	ds_read_b128 v[212:215], v207 offset:45600
	s_waitcnt lgkmcnt(9)
	v_mfma_f32_32x32x16_bf16 v[102:117], v[216:219], v[126:129], v[70:85]
	ds_read_b128 v[216:219], v207 offset:45632
	s_waitcnt lgkmcnt(9)
	v_mfma_f32_32x32x16_bf16 v[102:117], v[228:231], v[0:3], v[102:117]
	ds_read_b128 v[228:231], v207 offset:45664
	s_waitcnt lgkmcnt(9)
	v_mfma_f32_32x32x16_bf16 v[102:117], v[232:235], v[118:121], v[102:117]
	ds_read_b128 v[232:235], v207 offset:45696
	s_waitcnt lgkmcnt(9)
	v_mfma_f32_32x32x16_bf16 v[102:117], v[236:239], v[122:125], v[102:117]
	ds_read_b128 v[236:239], v207 offset:45728
	s_waitcnt lgkmcnt(9)
	v_mfma_f32_32x32x16_bf16 v[102:117], v[240:243], v[130:133], v[102:117]
	ds_read_b128 v[240:243], v207 offset:45760
	s_waitcnt lgkmcnt(9)
	v_mfma_f32_32x32x16_bf16 v[102:117], v[244:247], v[134:137], v[102:117]
	ds_read_b128 v[244:247], v207 offset:45792
	s_waitcnt lgkmcnt(9)
	v_mfma_f32_32x32x16_bf16 v[102:117], v[248:251], v[138:141], v[102:117]
	s_waitcnt lgkmcnt(8)
	v_mfma_f32_32x32x16_bf16 v[102:117], v[222:225], v[142:145], v[102:117]
	s_waitcnt lgkmcnt(7)
	v_mfma_f32_32x32x16_bf16 v[86:101], v[208:211], v[126:129], v[70:85]
	s_waitcnt lgkmcnt(6)
	v_mfma_f32_32x32x16_bf16 v[86:101], v[212:215], v[0:3], v[86:101]
	s_waitcnt lgkmcnt(5)
	v_mfma_f32_32x32x16_bf16 v[86:101], v[216:219], v[118:121], v[86:101]
	ds_read_b128 v[248:251], v204 offset:0
	ds_read_b128 v[222:225], v204 offset:32
	ds_read_b128 v[216:219], v204 offset:4608
	s_waitcnt lgkmcnt(7)
	v_mfma_f32_32x32x16_bf16 v[86:101], v[228:231], v[122:125], v[86:101]
	ds_read_b128 v[228:231], v204 offset:4640
	s_waitcnt lgkmcnt(7)
	v_mfma_f32_32x32x16_bf16 v[86:101], v[232:235], v[130:133], v[86:101]
	ds_read_b128 v[232:235], v204 offset:9216
	s_waitcnt lgkmcnt(7)
	v_mfma_f32_32x32x16_bf16 v[86:101], v[236:239], v[134:137], v[86:101]
	ds_read_b128 v[236:239], v204 offset:9248
	s_waitcnt lgkmcnt(7)
	v_mfma_f32_32x32x16_bf16 v[86:101], v[240:243], v[138:141], v[86:101]
	ds_read_b128 v[240:243], v204 offset:13824
	s_waitcnt lgkmcnt(7)
	v_mfma_f32_32x32x16_bf16 v[86:101], v[244:247], v[142:145], v[86:101]
	ds_read_b128 v[244:247], v204 offset:13856
	v_lshrrev_b64 v[208:209], v182, v[220:221]
	v_exp_f32_e32 v102, v102
	v_bfe_i32 v209, v208, 0, 1
	v_exp_f32_e32 v103, v103
	v_bfe_i32 v210, v208, 1, 1
	v_and_b32_e32 v102, v102, v209
	v_exp_f32_e32 v104, v104
	v_bfe_i32 v211, v208, 2, 1
	v_and_b32_e32 v103, v103, v210
	v_exp_f32_e32 v105, v105
	v_bfe_i32 v209, v208, 3, 1
	v_and_b32_e32 v104, v104, v211
	v_exp_f32_e32 v106, v106
	v_bfe_i32 v210, v208, 8, 1
	v_and_b32_e32 v105, v105, v209
	v_exp_f32_e32 v107, v107
	v_bfe_i32 v211, v208, 9, 1
	v_and_b32_e32 v106, v106, v210
	v_exp_f32_e32 v108, v108
	v_bfe_i32 v209, v208, 10, 1
	v_and_b32_e32 v107, v107, v211
	v_exp_f32_e32 v109, v109
	v_bfe_i32 v210, v208, 11, 1
	v_and_b32_e32 v108, v108, v209
	v_exp_f32_e32 v110, v110
	v_bfe_i32 v211, v208, 16, 1
	v_and_b32_e32 v109, v109, v210
	v_exp_f32_e32 v111, v111
	v_bfe_i32 v209, v208, 17, 1
	v_and_b32_e32 v110, v110, v211
	v_exp_f32_e32 v112, v112
	v_bfe_i32 v210, v208, 18, 1
	v_and_b32_e32 v111, v111, v209
	v_exp_f32_e32 v113, v113
	v_bfe_i32 v211, v208, 19, 1
	v_and_b32_e32 v112, v112, v210
	v_exp_f32_e32 v114, v114
	v_bfe_i32 v209, v208, 24, 1
	v_and_b32_e32 v113, v113, v211
	v_exp_f32_e32 v115, v115
	v_bfe_i32 v210, v208, 25, 1
	v_and_b32_e32 v114, v114, v209
	v_exp_f32_e32 v116, v116
	v_bfe_i32 v211, v208, 26, 1
	v_and_b32_e32 v115, v115, v210
	v_exp_f32_e32 v117, v117
	v_bfe_i32 v209, v208, 27, 1
	v_and_b32_e32 v116, v116, v211
	s_nop 0
	v_and_b32_e32 v117, v117, v209
	v_cvt_pk_bf16_f32 v208, v102, v103
	v_cvt_pk_bf16_f32 v209, v104, v105
	v_cvt_pk_bf16_f32 v210, v106, v107
	v_cvt_pk_bf16_f32 v211, v108, v109
	v_cvt_pk_bf16_f32 v212, v110, v111
	v_cvt_pk_bf16_f32 v213, v112, v113
	v_cvt_pk_bf16_f32 v214, v114, v115
	v_cvt_pk_bf16_f32 v215, v116, v117
	s_nop 1
	s_waitcnt lgkmcnt(7)
	v_mfma_f32_32x32x16_bf16 v[54:69], v[248:251], v[208:211], v[54:69]
	ds_read_b128 v[248:251], v204 offset:64
	v_add_f32_e32 v194, v194, v102
	v_add_f32_e32 v194, v103, v194
	s_waitcnt lgkmcnt(7)
; #define LAS __attribute__((address_space(3)))
; __device__ __forceinline__ unsigned pk2(float lo, float hi) { f32x2_t v = {lo, hi}; bf16x2_t b = __builtin_convertvector(v, bf16x2_t); return __builtin_bit_cast(unsigned, b); }
; __device__ __forceinline__ f32x16 mfma32(bf16x8 a, bf16x8 b, f32x16 c) { return __builtin_amdgcn_mfma_f32_32x32x16_bf16(a, b, c, 0, 0, 0); }
; __device__ __forceinline__ void dsa_unit32(const Args& a, LAS unsigned char* lds, const LAS unsigned long long* maskl, int b, int qb, int tid, int wave, int lane) {
;     ...
;         for (int kh = 0; kh < 2; ++kh) {
;             const unsigned mh = (unsigned)(mw >> (32 * kh + 4 * hi));
;             float p[16];
; #pragma unroll
;             for (int i = 0; i < 16; ++i) { const float e = __builtin_amdgcn_exp2f(S2[kh][i]);
;                 const int keep = __builtin_amdgcn_sbfe((int)mh, 8 * (i >> 2) + (i & 3), 1);
;                 p[i] = __builtin_bit_cast(float, __builtin_bit_cast(int, e) & keep); l += p[i]; }
;             u32x4 w0, w1;
;             w0.x = pk2(p[0], p[1]); w0.y = pk2(p[2], p[3]); w0.z = pk2(p[4], p[5]); w0.w = pk2(p[6], p[7]);
;             w1.x = pk2(p[8], p[9]); w1.y = pk2(p[10], p[11]); w1.z = pk2(p[12], p[13]); w1.w = pk2(p[14], p[15]);
;             const bf16x8 pa = __builtin_bit_cast(bf16x8, w0), pb = __builtin_bit_cast(bf16x8, w1);
;             __builtin_amdgcn_s_setprio(1);
; #pragma unroll
;             for (int ct = 0; ct < 4; ++ct) {
;                 const LAS bf16* vr = Vs + (32 * ct + l31) * VS + 4 * hi + 32 * kh;
;                 O[ct] = mfma32(cat8(*(const LAS u32x2*)(vr), *(const LAS u32x2*)(vr + 8)), pa, O[ct]);
;                 O[ct] = mfma32(cat8(*(const LAS u32x2*)(vr + 16), *(const LAS u32x2*)(vr + 24)), pb, O[ct]);
;             }
;             __builtin_amdgcn_s_setprio(0);
;         }
;     };
;     DSA_GLOAD(0, rk0, rv0); if (nkt > 1) DSA_GLOAD(1, rk1, rv1);
;     DSA_LSTORE(0, rk0, rv0);
;     __syncthreads();
; #pragma unroll 1
;     for (int kt = 0; kt < nkt; kt += 2) {
;         if (kt + 2 < nkt) DSA_GLOAD(kt + 2, rk0, rv0);
;         compute(0, kt);
;         if (kt + 1 < nkt) DSA_LSTORE(1, rk1, rv1);
;         __syncthreads();
;         if (kt + 1 >= nkt) break;
;         if (kt + 3 < nkt) DSA_GLOAD(kt + 3, rk1, rv1);
;         compute(1, kt + 1);
;         if (kt + 2 < nkt) DSA_LSTORE(0, rk0, rv0);
;         __syncthreads();
;     }
	v_mfma_f32_32x32x16_bf16 v[54:69], v[222:225], v[212:215], v[54:69]
	ds_read_b128 v[222:225], v204 offset:96
	v_add_f32_e32 v194, v104, v194
	v_add_f32_e32 v194, v105, v194
	s_waitcnt lgkmcnt(7)
	v_mfma_f32_32x32x16_bf16 v[38:53], v[216:219], v[208:211], v[38:53]
	ds_read_b128 v[216:219], v204 offset:4672
	v_add_f32_e32 v194, v106, v194
	v_add_f32_e32 v194, v107, v194
	s_waitcnt lgkmcnt(7)
	v_mfma_f32_32x32x16_bf16 v[38:53], v[228:231], v[212:215], v[38:53]
	ds_read_b128 v[228:231], v204 offset:4704
	v_add_f32_e32 v194, v108, v194
	v_add_f32_e32 v194, v109, v194
	s_waitcnt lgkmcnt(7)
	v_mfma_f32_32x32x16_bf16 v[22:37], v[232:235], v[208:211], v[22:37]
	ds_read_b128 v[232:235], v204 offset:9280
	v_add_f32_e32 v194, v110, v194
	v_add_f32_e32 v194, v111, v194
	s_waitcnt lgkmcnt(7)
	v_mfma_f32_32x32x16_bf16 v[22:37], v[236:239], v[212:215], v[22:37]
	ds_read_b128 v[236:239], v204 offset:9312
	v_add_f32_e32 v194, v112, v194
	v_add_f32_e32 v194, v113, v194
	s_waitcnt lgkmcnt(7)
	v_mfma_f32_32x32x16_bf16 v[6:21], v[240:243], v[208:211], v[6:21]
	ds_read_b128 v[240:243], v204 offset:13888
	v_add_f32_e32 v194, v114, v194
	v_add_f32_e32 v194, v115, v194
	s_waitcnt lgkmcnt(7)
	v_mfma_f32_32x32x16_bf16 v[6:21], v[244:247], v[212:215], v[6:21]
	ds_read_b128 v[244:247], v204 offset:13920
	v_add_f32_e32 v194, v116, v194
	v_add_f32_e32 v194, v117, v194
	v_lshrrev_b64 v[208:209], v184, v[220:221]
	v_exp_f32_e32 v86, v86
	v_bfe_i32 v209, v208, 0, 1
	v_exp_f32_e32 v87, v87
	v_bfe_i32 v210, v208, 1, 1
	v_and_b32_e32 v86, v86, v209
	v_exp_f32_e32 v88, v88
	v_bfe_i32 v211, v208, 2, 1
	v_and_b32_e32 v87, v87, v210
	v_exp_f32_e32 v89, v89
	v_bfe_i32 v209, v208, 3, 1
	v_and_b32_e32 v88, v88, v211
	v_exp_f32_e32 v90, v90
	v_bfe_i32 v210, v208, 8, 1
	v_and_b32_e32 v89, v89, v209
	v_exp_f32_e32 v91, v91
	v_bfe_i32 v211, v208, 9, 1
	v_and_b32_e32 v90, v90, v210
	v_exp_f32_e32 v92, v92
	v_bfe_i32 v209, v208, 10, 1
	v_and_b32_e32 v91, v91, v211
	v_exp_f32_e32 v93, v93
	v_bfe_i32 v210, v208, 11, 1
	v_and_b32_e32 v92, v92, v209
	v_exp_f32_e32 v94, v94
	v_bfe_i32 v211, v208, 16, 1
	v_and_b32_e32 v93, v93, v210
	v_exp_f32_e32 v95, v95
	v_bfe_i32 v209, v208, 17, 1
	v_and_b32_e32 v94, v94, v211
	v_exp_f32_e32 v96, v96
	v_bfe_i32 v210, v208, 18, 1
	v_and_b32_e32 v95, v95, v209
	v_exp_f32_e32 v97, v97
	v_bfe_i32 v211, v208, 19, 1
	v_and_b32_e32 v96, v96, v210
	v_exp_f32_e32 v98, v98
	v_bfe_i32 v209, v208, 24, 1
	v_and_b32_e32 v97, v97, v211
	v_exp_f32_e32 v99, v99
	v_bfe_i32 v210, v208, 25, 1
	v_and_b32_e32 v98, v98, v209
	v_exp_f32_e32 v100, v100
	v_bfe_i32 v211, v208, 26, 1
	v_and_b32_e32 v99, v99, v210
	v_exp_f32_e32 v101, v101
	v_bfe_i32 v209, v208, 27, 1
	v_and_b32_e32 v100, v100, v211
	s_nop 0
	v_and_b32_e32 v101, v101, v209
	v_cvt_pk_bf16_f32 v208, v86, v87
	v_cvt_pk_bf16_f32 v209, v88, v89
	v_cvt_pk_bf16_f32 v210, v90, v91
	v_cvt_pk_bf16_f32 v211, v92, v93
	v_cvt_pk_bf16_f32 v212, v94, v95
	v_cvt_pk_bf16_f32 v213, v96, v97
	v_cvt_pk_bf16_f32 v214, v98, v99
	v_cvt_pk_bf16_f32 v215, v100, v101
	s_nop 1
	s_waitcnt lgkmcnt(7)
	v_mfma_f32_32x32x16_bf16 v[54:69], v[248:251], v[208:211], v[54:69]
	v_add_f32_e32 v194, v194, v86
	v_add_f32_e32 v194, v87, v194
	s_waitcnt lgkmcnt(6)
	v_mfma_f32_32x32x16_bf16 v[54:69], v[222:225], v[212:215], v[54:69]
	v_add_f32_e32 v194, v88, v194
	v_add_f32_e32 v194, v89, v194
	s_waitcnt lgkmcnt(5)
	v_mfma_f32_32x32x16_bf16 v[38:53], v[216:219], v[208:211], v[38:53]
	v_add_f32_e32 v194, v90, v194
	v_add_f32_e32 v194, v91, v194
	s_waitcnt lgkmcnt(4)
	v_mfma_f32_32x32x16_bf16 v[38:53], v[228:231], v[212:215], v[38:53]
	v_add_f32_e32 v194, v92, v194
	v_add_f32_e32 v194, v93, v194
	s_waitcnt lgkmcnt(3)
	v_mfma_f32_32x32x16_bf16 v[22:37], v[232:235], v[208:211], v[22:37]
	v_add_f32_e32 v194, v94, v194
	v_add_f32_e32 v194, v95, v194
	s_waitcnt lgkmcnt(2)
	v_mfma_f32_32x32x16_bf16 v[22:37], v[236:239], v[212:215], v[22:37]
	v_add_f32_e32 v194, v96, v194
	v_add_f32_e32 v194, v97, v194
	s_waitcnt lgkmcnt(1)
	v_mfma_f32_32x32x16_bf16 v[6:21], v[240:243], v[208:211], v[6:21]
	v_add_f32_e32 v194, v98, v194
	v_add_f32_e32 v194, v99, v194
	s_waitcnt lgkmcnt(0)
	v_mfma_f32_32x32x16_bf16 v[6:21], v[244:247], v[212:215], v[6:21]
	v_add_f32_e32 v194, v100, v194
	v_add_f32_e32 v194, v101, v194
	s_andn2_b64 vcc, exec, s[0:1]
	s_cbranch_vccnz .LBB0_1301
	s_waitcnt vmcnt(3)
	ds_write_b128 v196, v[146:149]
	s_waitcnt vmcnt(1)
	ds_write2_b64 v198, v[154:155], v[156:157] offset1:2
	ds_write_b128 v199, v[150:153]
	s_waitcnt vmcnt(0)
	ds_write2_b64 v201, v[158:159], v[160:161] offset1:2
	s_branch .LBB0_1301
